# in-proj: next tile's first K-tile LDS-DMA loads issued before the epilogue stores; C16 staging remapped to free LDS
# baseline (speedup 1.0000x reference)
.LBB0_127:
	v_readlane_b32 s0, v255, 0
	s_and_b32 s44, s0, 7
	s_lshr_b32 s87, s0, 3
	s_bfe_u32 s1, s0, 0x20003
	s_lshr_b32 s45, s0, 5
	v_writelane_b32 v255, s1, 7
	s_add_u32 s0, s78, 0x30000
	v_writelane_b32 v255, s0, 8
	s_addc_u32 s47, s79, 0
	s_mov_b32 s5, 0
	v_mov_b32_e32 v133, 0
	s_add_i32 s33, 16, 0x10000
	s_add_i32 s84, 16, 0x14000
	s_mov_b64 s[6:7], 0x80
	s_add_i32 s85, 16, 0x18000
	s_add_i32 s86, 16, 0x1c000
	s_mov_b64 s[8:9], 0x80080
	s_mov_b64 s[10:11], 0x100
	s_mov_b64 s[14:15], 0x80100
	s_mov_b64 s[16:17], 0x180
	s_mov_b64 s[24:25], 0x80180
	s_movk_i32 s89, 0x210
	s_movk_i32 s90, 0x110
	v_mov_b32_e32 v141, 1
	v_mov_b32_e32 v142, 0x3e0293ee
	v_mbcnt_hi_u32_b32 v188, -1, v1
	s_mov_b32 s91, 0
	s_mov_b32 s101, 0
	v_mov_b32_e32 v205, 0x8000
	v_mov_b32_e32 v254, 0x10020
	v_cmp_lt_u32_e32 vcc, 255, v204
	s_nop 1
	v_cndmask_b32_e32 v205, v205, v254, vcc
	v_and_b32_e32 v254, 0x10e, v204
	v_cmp_eq_u32_e32 vcc, 14, v254
	v_mov_b32_e32 v254, 0x8020
	s_nop 1
	v_cndmask_b32_e32 v254, 0, v254, vcc
	s_branch .LBB0_130
.Lip_pf_path:
	v_add_u32_e32 v147, s33, v17
	v_ashrrev_i32_e32 v16, 6, v2
	v_and_b32_e32 v2, 0xc0, v2
	s_add_u32 s2, s54, s30
	v_add_u32_e32 v148, 0x2000, v147
	v_sub_u32_e32 v0, v0, v2
	s_addc_u32 s3, s55, s31
	v_lshlrev_b32_e32 v1, 3, v14
	v_lshlrev_b32_e32 v3, 5, v14
	v_ashrrev_i16_sdwa v0, v141, sext(v0) dst_sel:DWORD dst_unused:UNUSED_PAD src0_sel:DWORD src1_sel:BYTE_0
	s_lshl_b32 s1, s34, 20
	v_and_b32_e32 v1, 0xffff0, v1
	v_and_b32_e32 v3, 32, v3
	v_bfe_i32 v18, v0, 0, 16
	s_add_u32 s28, s52, s1
	v_add_u32_e32 v0, v3, v18
	v_add_lshl_u32 v1, v16, v1, 12
	s_addc_u32 s29, s53, 0
	v_add_u32_e32 v150, 16, v17
	s_or_b32 s36, s0, 0x80
	v_lshl_add_u32 v128, v0, 1, v1
	v_add_u32_e32 v151, 0x2000, v150
	s_ashr_i32 s37, s36, 31
	s_lshl_b64 s[36:37], s[36:37], 12
	v_add_u32_e32 v152, s84, v17
	s_add_u32 s36, s54, s36
	v_add_u32_e32 v153, 0x2000, v152
	s_addc_u32 s37, s55, s37
	v_add_u32_e32 v155, 0x4000, v150
	s_add_u32 s42, s28, 0x80000
	v_add_u32_e32 v156, 0x6000, v150
	s_addc_u32 s43, s29, 0
	v_ashrrev_i32_e32 v19, 8, v140
	s_branch .Lip_pf_join

.LBB0_130:
	v_mov_b32_e32 v140, v204
	s_lshl_b32 s0, s91, 3
	s_waitcnt lgkmcnt(0)
	v_ashrrev_i32_e32 v0, 31, v140
	v_lshrrev_b32_e32 v0, 26, v0
	v_add_u32_e32 v0, v140, v0
	v_ashrrev_i32_e32 v12, 6, v0
	v_bfe_i32 v0, v140, 27, 1
	v_lshlrev_b32_e32 v17, 4, v140
	v_lshrrev_b32_e32 v0, 22, v0
	v_add_u32_e32 v0, v17, v0
	v_and_b32_e32 v0, 0xfffffc00, v0
	v_sub_u32_e32 v0, v17, v0
	v_lshrrev_b32_e32 v1, 4, v0
	v_bitop3_b32 v0, v1, v0, 32 bitop3:0x6c
	v_ashrrev_i32_e32 v2, 31, v0
	v_lshrrev_b32_e32 v2, 26, v2
	v_add_u32_e32 v2, v0, v2
	v_ashrrev_i32_e32 v13, 6, v2
	v_and_b32_e32 v2, 0xc0, v2
	v_sub_u32_e32 v0, v0, v2
	v_lshlrev_b32_e32 v1, 3, v12
	v_lshlrev_b32_e32 v3, 5, v12
	v_ashrrev_i16_sdwa v0, v141, sext(v0) dst_sel:DWORD dst_unused:UNUSED_PAD src0_sel:DWORD src1_sel:BYTE_0
	v_and_b32_e32 v1, 0xffff0, v1
	v_and_b32_e32 v3, 32, v3
	v_bfe_i32 v15, v0, 0, 16
	v_add_u32_e32 v0, v3, v15
	v_add_lshl_u32 v1, v13, v1, 12
	s_or_b32 s0, s0, s44
	v_lshl_add_u32 v132, v0, 1, v1
	v_mov_b32_e32 v189, v132
	v_add_u32_e32 v0, 0x2000, v17
	s_and_b32 s1, s0, 0xff
	v_ashrrev_i32_e32 v1, 31, v0
	s_mulk_i32 s1, 0xab
	v_lshrrev_b32_e32 v1, 22, v1
	s_lshr_b32 s2, s1, 9
	v_add_u32_e32 v1, v0, v1
	s_mul_i32 s2, s2, 3
	v_ashrrev_i32_e32 v14, 10, v1
	s_sub_i32 s0, s0, s2
	v_mul_i32_i24_e32 v1, 0x400, v14
	s_lshl_b32 s0, s0, 3
	v_sub_u32_e32 v0, v0, v1
	s_and_b32 s0, s0, 0xf8
	v_lshrrev_b32_e32 v1, 4, v0
	s_lshr_b32 s1, s1, 7
	s_add_i32 s96, s45, s0
	v_bitop3_b32 v0, v1, v0, 32 bitop3:0x6c
	s_and_b32 s4, s1, 0xfc
	v_readlane_b32 s1, v255, 7
	s_lshl_b32 s0, s96, 8
	v_ashrrev_i32_e32 v2, 31, v0
	s_or_b32 s34, s1, s4
	v_lshrrev_b32_e32 v2, 26, v2
	s_ashr_i32 s1, s0, 31
	v_add_u32_e32 v2, v0, v2
	s_lshl_b64 s[30:31], s[0:1], 12
	s_cmp_lg_u32 s101, 0
	s_cbranch_scc1 .Lip_pf_path
	v_add_u32_e32 v147, s33, v17
	v_ashrrev_i32_e32 v16, 6, v2
	v_and_b32_e32 v2, 0xc0, v2
	s_add_u32 s2, s54, s30
	v_readfirstlane_b32 s1, v147
	v_add_u32_e32 v148, 0x2000, v147
	v_sub_u32_e32 v0, v0, v2
	s_addc_u32 s3, s55, s31
	s_mov_b32 m0, s1
	v_readfirstlane_b32 s1, v148
	v_lshlrev_b32_e32 v1, 3, v14
	v_lshlrev_b32_e32 v3, 5, v14
	v_ashrrev_i16_sdwa v0, v141, sext(v0) dst_sel:DWORD dst_unused:UNUSED_PAD src0_sel:DWORD src1_sel:BYTE_0
	global_load_lds_dwordx4 v132, s[2:3]
	s_mov_b32 m0, s1
	s_lshl_b32 s1, s34, 20
	v_and_b32_e32 v1, 0xffff0, v1
	v_and_b32_e32 v3, 32, v3
	v_bfe_i32 v18, v0, 0, 16
	s_add_u32 s28, s52, s1
	v_add_u32_e32 v0, v3, v18
	v_add_lshl_u32 v1, v16, v1, 12
	s_addc_u32 s29, s53, 0
	v_add_u32_e32 v150, 16, v17
	s_or_b32 s36, s0, 0x80
	v_lshl_add_u32 v128, v0, 1, v1
	v_readfirstlane_b32 s1, v150
	v_add_u32_e32 v151, 0x2000, v150
	s_ashr_i32 s37, s36, 31
	global_load_lds_dwordx4 v128, s[2:3]
	s_mov_b32 m0, s1
	v_readfirstlane_b32 s1, v151
	s_lshl_b64 s[36:37], s[36:37], 12
	v_add_u32_e32 v152, s84, v17
	global_load_lds_dwordx4 v132, s[28:29]
	s_mov_b32 m0, s1
	s_add_u32 s36, s54, s36
	v_readfirstlane_b32 s1, v152
	v_add_u32_e32 v153, 0x2000, v152
	global_load_lds_dwordx4 v128, s[28:29]
	s_addc_u32 s37, s55, s37
	s_mov_b32 m0, s1
	v_readfirstlane_b32 s1, v153
	v_add_u32_e32 v155, 0x4000, v150
	global_load_lds_dwordx4 v132, s[36:37]
	s_mov_b32 m0, s1
	s_add_u32 s42, s28, 0x80000
	v_readfirstlane_b32 s1, v155
	v_add_u32_e32 v156, 0x6000, v150
	global_load_lds_dwordx4 v128, s[36:37]
	s_addc_u32 s43, s29, 0
	s_mov_b32 m0, s1
	v_readfirstlane_b32 s1, v156
	global_load_lds_dwordx4 v132, s[42:43]
	s_mov_b32 m0, s1
	v_ashrrev_i32_e32 v19, 8, v140
	global_load_lds_dwordx4 v128, s[42:43]
.Lip_pf_join:
	v_mov_b32_e32 v129, v133
	v_lshl_add_u64 v[10:11], s[2:3], 0, v[132:133]
	v_lshl_add_u64 v[8:9], s[2:3], 0, v[128:129]
	v_lshl_add_u64 v[6:7], s[28:29], 0, v[132:133]
	v_lshl_add_u64 v[4:5], s[28:29], 0, v[128:129]
	v_lshl_add_u64 v[2:3], s[36:37], 0, v[132:133]
	v_lshl_add_u64 v[0:1], s[36:37], 0, v[128:129]
	v_cmp_eq_u32_e32 vcc, 1, v19
	s_and_saveexec_b64 s[2:3], vcc
	s_cbranch_execz .LBB0_132
	s_barrier
.LBB0_132:
	s_or_b64 exec, exec, s[2:3]
	v_mov_b32_e32 v22, 0
	v_mov_b32_e32 v23, 0
	v_mov_b32_e32 v24, 0
	v_mov_b32_e32 v25, 0
	v_mov_b32_e32 v26, 0
	v_mov_b32_e32 v27, 0
	v_mov_b32_e32 v28, 0
	v_mov_b32_e32 v29, 0
	v_mov_b32_e32 v30, 0
	v_mov_b32_e32 v31, 0
	v_mov_b32_e32 v32, 0
	v_mov_b32_e32 v33, 0
	v_mov_b32_e32 v34, 0
	v_mov_b32_e32 v35, 0
	v_mov_b32_e32 v36, 0
	v_mov_b32_e32 v37, 0
	v_mov_b32_e32 v38, 0
	v_mov_b32_e32 v39, 0
	v_mov_b32_e32 v40, 0
	v_mov_b32_e32 v41, 0
	v_mov_b32_e32 v42, 0
	v_mov_b32_e32 v43, 0
	v_mov_b32_e32 v44, 0
	v_mov_b32_e32 v45, 0
	v_mov_b32_e32 v46, 0
	v_mov_b32_e32 v47, 0
	v_mov_b32_e32 v48, 0
	v_mov_b32_e32 v49, 0
	v_mov_b32_e32 v50, 0
	v_mov_b32_e32 v51, 0
	v_mov_b32_e32 v52, 0
	v_mov_b32_e32 v53, 0
	v_mov_b32_e32 v54, 0
	v_mov_b32_e32 v55, 0
	v_mov_b32_e32 v56, 0
	v_mov_b32_e32 v57, 0
	v_mov_b32_e32 v58, 0
	v_mov_b32_e32 v59, 0
	v_mov_b32_e32 v60, 0
	v_mov_b32_e32 v61, 0
	v_mov_b32_e32 v62, 0
	v_mov_b32_e32 v63, 0
	v_mov_b32_e32 v64, 0
	v_mov_b32_e32 v65, 0
	v_mov_b32_e32 v66, 0
	v_mov_b32_e32 v67, 0
	v_mov_b32_e32 v68, 0
	v_mov_b32_e32 v69, 0
	v_mov_b32_e32 v70, 0
	v_mov_b32_e32 v71, 0
	v_mov_b32_e32 v72, 0
	v_mov_b32_e32 v73, 0
	v_mov_b32_e32 v74, 0
	v_mov_b32_e32 v75, 0
	v_mov_b32_e32 v76, 0
	v_mov_b32_e32 v77, 0
	v_mov_b32_e32 v78, 0
	v_mov_b32_e32 v79, 0
	v_mov_b32_e32 v80, 0
	v_mov_b32_e32 v81, 0
	v_mov_b32_e32 v82, 0
	v_mov_b32_e32 v83, 0
	v_mov_b32_e32 v84, 0
	v_mov_b32_e32 v85, 0
	v_mov_b32_e32 v86, 0
	v_mov_b32_e32 v87, 0
	v_mov_b32_e32 v88, 0
	v_mov_b32_e32 v89, 0
	v_mov_b32_e32 v90, 0
	v_mov_b32_e32 v91, 0
	v_mov_b32_e32 v92, 0
	v_mov_b32_e32 v93, 0
	v_mov_b32_e32 v94, 0
	v_mov_b32_e32 v95, 0
	v_mov_b32_e32 v96, 0
	v_mov_b32_e32 v97, 0
	v_mov_b32_e32 v98, 0
	v_mov_b32_e32 v99, 0
	v_mov_b32_e32 v100, 0
	v_mov_b32_e32 v101, 0
	v_mov_b32_e32 v102, 0
	v_mov_b32_e32 v103, 0
	v_mov_b32_e32 v104, 0
	v_mov_b32_e32 v105, 0
	v_mov_b32_e32 v106, 0
	v_mov_b32_e32 v107, 0
	v_mov_b32_e32 v108, 0
	v_mov_b32_e32 v109, 0
	v_mov_b32_e32 v110, 0
	v_mov_b32_e32 v111, 0
	v_mov_b32_e32 v112, 0
	v_mov_b32_e32 v113, 0
	v_mov_b32_e32 v114, 0
	v_mov_b32_e32 v115, 0
	v_mov_b32_e32 v116, 0
	v_mov_b32_e32 v117, 0
	v_mov_b32_e32 v118, 0
	v_mov_b32_e32 v119, 0
	v_mov_b32_e32 v120, 0
	v_mov_b32_e32 v121, 0
	v_mov_b32_e32 v122, 0
	v_mov_b32_e32 v123, 0
	v_mov_b32_e32 v124, 0
	v_mov_b32_e32 v125, 0
	v_mov_b32_e32 v126, 0
	v_mov_b32_e32 v127, 0
	v_add_u32_e32 v157, s85, v17
	v_add_u32_e32 v158, 0x2000, v157
	v_readfirstlane_b32 s1, v157
	v_lshl_add_u64 v[10:11], v[10:11], 0, s[6:7]
	s_mov_b32 m0, s1
	v_readfirstlane_b32 s1, v158
	v_add_u32_e32 v159, 0x8000, v150
	s_cmp_lg_u32 s101, 0
	s_cbranch_scc1 .Lip_w1_pf
	s_waitcnt vmcnt(4)
	s_branch .Lip_w1_done
.Lip_w1_pf:
	s_waitcnt vmcnt(20)
.Lip_w1_done:
	s_barrier
	global_load_lds_dwordx4 v[10:11], off
	v_lshl_add_u64 v[8:9], v[8:9], 0, s[6:7]
	s_mov_b32 m0, s1
	v_readfirstlane_b32 s1, v159
	v_add_u32_e32 v160, 0xa000, v150
	global_load_lds_dwordx4 v[8:9], off
	v_lshl_add_u64 v[6:7], v[6:7], 0, s[6:7]
	s_mov_b32 m0, s1
	v_readfirstlane_b32 s1, v160
	v_add_u32_e32 v161, s86, v17
	global_load_lds_dwordx4 v[6:7], off
	v_lshl_add_u64 v[4:5], v[4:5], 0, s[6:7]
	s_mov_b32 m0, s1
	v_readfirstlane_b32 s1, v161
	v_add_u32_e32 v162, 0x2000, v161
	global_load_lds_dwordx4 v[4:5], off
	v_lshl_add_u64 v[2:3], v[2:3], 0, s[6:7]
	s_mov_b32 m0, s1
	v_readfirstlane_b32 s1, v162
	global_load_lds_dwordx4 v[2:3], off
	v_lshl_add_u64 v[0:1], v[0:1], 0, s[6:7]
	s_mov_b32 m0, s1
	v_and_b32_e32 v20, 15, v140
	global_load_lds_dwordx4 v[0:1], off
	v_lshlrev_b32_e32 v1, 2, v140
	v_and_b32_e32 v21, 48, v140
	v_lshlrev_b32_e32 v0, 6, v20
	v_and_b32_e32 v1, 32, v1
	v_bitop3_b32 v0, v0, v1, v21 bitop3:0x36
	v_lshlrev_b32_e32 v2, 6, v140
	s_movk_i32 s1, 0x3c0
	v_add_u32_e32 v4, s33, v0
	v_add_u32_e32 v5, s84, v0
	v_add_u32_e32 v6, s85, v0
	v_add_u32_e32 v7, s86, v0
	v_add_u32_e32 v10, 16, v0
	v_and_or_b32 v0, v2, s1, v21
	v_and_b32_e32 v8, 0x3000, v2
	v_xad_u32 v11, v0, v1, 16
	v_lshlrev_b32_e32 v0, 15, v12
	v_lshlrev_b32_e32 v2, 15, v14
	v_and_b32_e32 v0, 0xffff0000, v0
	v_and_b32_e32 v2, 0xffff0000, v2
	v_lshl_add_u32 v0, v13, 12, v0
	v_and_b32_e32 v1, 1, v12
	s_add_u32 s2, s54, s30
	v_lshl_add_u32 v2, v16, 12, v2
	v_and_b32_e32 v3, 1, v14
	v_readlane_b32 s1, v255, 7
	v_lshl_or_b32 v0, v1, 6, v0
	s_addc_u32 s3, s55, s31
	v_lshl_or_b32 v2, v3, 6, v2
	s_add_i32 s1, s1, s4
	v_lshl_add_u32 v0, v15, 1, v0
	v_mov_b32_e32 v1, v133
	v_lshl_add_u32 v2, v18, 1, v2
	v_mov_b32_e32 v3, v133
	s_lshl_b32 s1, s1, 20
	v_lshl_add_u64 v[130:131], s[2:3], 0, v[0:1]
	v_lshl_add_u64 v[134:135], s[2:3], 0, v[2:3]
	s_add_u32 s2, s52, s1
	v_lshlrev_b32_e32 v9, 13, v19
	s_addc_u32 s3, s53, 0
	s_cmp_lg_u32 s101, 0
	s_cbranch_scc1 .Lip_w2_pf
	s_waitcnt vmcnt(6)
	s_branch .Lip_w2_done
.Lip_w2_pf:
	s_waitcnt vmcnt(22)
.Lip_w2_done:
	v_or_b32_e32 v17, 0x800, v9
	v_or_b32_e32 v19, 0x1000, v9
	v_or_b32_e32 v20, 0x1800, v9
	v_lshl_add_u64 v[136:137], s[2:3], 0, v[0:1]
	v_mov_b32_e32 v0, 0
	v_lshl_add_u64 v[138:139], s[2:3], 0, v[2:3]
	s_mov_b32 s1, -2
	s_mov_b64 s[30:31], 0
	v_add_u32_e32 v164, v4, v8
	v_add_u32_e32 v146, v10, v9
	v_add_u32_e32 v145, v11, v17
	v_add_u32_e32 v144, v11, v19
	v_add_u32_e32 v143, v11, v20
	v_add_u32_e32 v163, v5, v8
	v_add_u32_e32 v154, v6, v8
	v_add_u32_e32 v149, v7, v8
	v_mov_b32_e32 v1, v0
	v_mov_b32_e32 v2, v0
	v_mov_b32_e32 v3, v0
	v_mov_b32_e32 v4, v0
	v_mov_b32_e32 v5, v0
	v_mov_b32_e32 v6, v0
	v_mov_b32_e32 v7, v0
	v_mov_b32_e32 v8, v0
	v_mov_b32_e32 v9, v0
	v_mov_b32_e32 v10, v0
	v_mov_b32_e32 v11, v0
	v_mov_b32_e32 v12, v0
	v_mov_b32_e32 v13, v0
	v_mov_b32_e32 v14, v0
	v_mov_b32_e32 v15, v0
	v_mov_b32_e32 v16, v0
	v_mov_b32_e32 v17, v0
	v_mov_b32_e32 v18, v0
	v_mov_b32_e32 v19, v0
	v_mov_b32_e32 v20, v0
	v_mov_b32_e32 v21, v0
	s_barrier

.LBB0_136:
	s_or_b64 exec, exec, s[2:3]
	s_lshl_b32 s97, s34, 8
	s_lshr_b32 s46, s96, 2
	s_and_b32 s88, s0, 0x300
	s_cmp_gt_u32 s96, 3
	v_mov_b32_e32 v135, v204
	s_cselect_b64 s[30:31], -1, 0
	s_cmp_lt_u32 s96, 4
	s_waitcnt vmcnt(0)
	s_barrier
	s_cselect_b64 vcc, -1, 0
	s_mov_b32 s101, 0
	s_cmp_eq_u32 s46, 2
	s_cbranch_scc1 .Lip_pf_done
	s_cmp_gt_u32 s91, 4
	s_cbranch_scc1 .Lip_pf_done
	s_add_i32 s98, s91, 1
	s_lshl_b32 s98, s98, 3
	s_or_b32 s98, s98, s44
	s_mul_i32 s99, s98, 0xab
	s_lshr_b32 s100, s99, 9
	s_mul_i32 s0, s100, 3
	s_sub_i32 s98, s98, s0
	s_lshl_b32 s98, s98, 3
	s_add_i32 s98, s45, s98
	s_lshl_b32 s100, s100, 2
	v_readlane_b32 s0, v255, 7
	s_lshl_b32 s98, s98, 20
	s_nop 0
	s_or_b32 s100, s0, s100
	s_lshl_b32 s100, s100, 20
	s_add_u32 s0, s54, s98
	s_addc_u32 s1, s55, 0
	s_add_u32 s2, s52, s100
	s_addc_u32 s3, s53, 0
	v_readfirstlane_b32 s98, v204
	v_add_u32_e32 v246, 0x40000, v189
	s_nop 0
	s_lshl_b32 s98, s98, 4
	s_add_i32 m0, s98, 0x10010
	s_nop 0
	global_load_lds_dwordx4 v189, s[0:1]
	s_add_i32 m0, s98, 0x12010
	s_nop 0
	global_load_lds_dwordx4 v246, s[0:1]
	s_add_i32 m0, s98, 0x10
	s_nop 0
	global_load_lds_dwordx4 v189, s[2:3]
	s_add_i32 m0, s98, 0x2010
	s_nop 0
	global_load_lds_dwordx4 v246, s[2:3]
	s_add_u32 s0, s0, 0x80000
	s_addc_u32 s1, s1, 0
	s_add_u32 s2, s2, 0x80000
	s_addc_u32 s3, s3, 0
	s_add_i32 m0, s98, 0x14010
	s_nop 0
	global_load_lds_dwordx4 v189, s[0:1]
	s_add_i32 m0, s98, 0x16010
	s_nop 0
	global_load_lds_dwordx4 v246, s[0:1]
	s_add_i32 m0, s98, 0x4010
	s_nop 0
	global_load_lds_dwordx4 v189, s[2:3]
	s_add_i32 m0, s98, 0x6010
	s_nop 0
	global_load_lds_dwordx4 v246, s[2:3]
	s_mov_b32 s101, 1
.Lip_pf_done:
	v_bfe_u32 v145, v135, 6, 2
	v_bfe_u32 v147, v135, 4, 2
	s_cmp_lg_u32 s46, 2
	v_lshlrev_b32_e32 v148, 3, v135
	v_ashrrev_i32_e32 v144, 8, v135
	v_and_b32_e32 v146, 15, v135
	s_cselect_b64 s[34:35], -1, 0
	s_cmp_eq_u32 s46, 1
	v_lshlrev_b32_e32 v128, 6, v145
	v_lshlrev_b32_e32 v129, 3, v147
	v_and_b32_e32 v143, 0xf8, v148
	v_cndmask_b32_e32 v136, 1.0, v142, vcc
	s_cselect_b64 s[28:29], -1, 0
	s_cmp_eq_u32 s46, 2
	v_lshl_or_b32 v160, v144, 6, v146
	v_add3_u32 v140, 16, v128, v129
	v_lshl_add_u32 v134, v143, 1, 16
	s_mov_b64 s[0:1], -1
	s_cbranch_scc1 .LBB0_164
	v_pk_mul_f32 v[130:131], v[136:137], v[124:125] op_sel_hi:[0,1]
	v_pk_mul_f32 v[138:139], v[136:137], v[126:127] op_sel_hi:[0,1]
	v_cvt_pk_bf16_f32 v130, v130, v131
	v_cvt_pk_bf16_f32 v131, v138, v139
	v_pk_mul_f32 v[138:139], v[136:137], v[120:121] op_sel_hi:[0,1]
	v_pk_mul_f32 v[150:151], v[136:137], v[122:123] op_sel_hi:[0,1]
	v_mad_u64_u32 v[128:129], s[0:1], v160, s89, v[140:141]
	v_add_u32_e32 v128, v128, v205
	v_cvt_pk_bf16_f32 v138, v138, v139
	v_cvt_pk_bf16_f32 v139, v150, v151
	ds_write2_b64 v128, v[130:131], v[138:139] offset1:4
	v_pk_mul_f32 v[130:131], v[136:137], v[116:117] op_sel_hi:[0,1]
	v_pk_mul_f32 v[138:139], v[136:137], v[118:119] op_sel_hi:[0,1]
	v_cvt_pk_bf16_f32 v130, v130, v131
	v_cvt_pk_bf16_f32 v131, v138, v139
	v_pk_mul_f32 v[138:139], v[136:137], v[112:113] op_sel_hi:[0,1]
	v_pk_mul_f32 v[150:151], v[136:137], v[114:115] op_sel_hi:[0,1]
	v_cvt_pk_bf16_f32 v138, v138, v139
	v_cvt_pk_bf16_f32 v139, v150, v151
	v_add_u32_e32 v132, 0x2000, v128
	ds_write2_b64 v132, v[130:131], v[138:139] offset0:32 offset1:36
	v_pk_mul_f32 v[130:131], v[136:137], v[108:109] op_sel_hi:[0,1]
	v_pk_mul_f32 v[138:139], v[136:137], v[110:111] op_sel_hi:[0,1]
	v_cvt_pk_bf16_f32 v130, v130, v131
	v_cvt_pk_bf16_f32 v131, v138, v139
	v_pk_mul_f32 v[138:139], v[136:137], v[104:105] op_sel_hi:[0,1]
	v_pk_mul_f32 v[150:151], v[136:137], v[106:107] op_sel_hi:[0,1]
	v_cvt_pk_bf16_f32 v138, v138, v139
	v_cvt_pk_bf16_f32 v139, v150, v151
	v_add_u32_e32 v137, 0x4000, v128
	ds_write2_b64 v137, v[130:131], v[138:139] offset0:64 offset1:68
	v_pk_mul_f32 v[130:131], v[136:137], v[100:101] op_sel_hi:[0,1]
	v_pk_mul_f32 v[138:139], v[136:137], v[102:103] op_sel_hi:[0,1]
	v_cvt_pk_bf16_f32 v130, v130, v131
	v_cvt_pk_bf16_f32 v131, v138, v139
	v_pk_mul_f32 v[138:139], v[136:137], v[92:93] op_sel_hi:[0,1]
	v_pk_mul_f32 v[150:151], v[136:137], v[94:95] op_sel_hi:[0,1]
	v_cvt_pk_bf16_f32 v138, v138, v139
	v_cvt_pk_bf16_f32 v139, v150, v151
	v_add_u32_e32 v149, 0x6000, v128
	v_add_u32_e32 v149, v149, v254
	ds_write2_b64 v149, v[130:131], v[138:139] offset0:96 offset1:100
	v_pk_mul_f32 v[130:131], v[136:137], v[96:97] op_sel_hi:[0,1]
	v_pk_mul_f32 v[138:139], v[136:137], v[98:99] op_sel_hi:[0,1]
	v_cvt_pk_bf16_f32 v130, v130, v131
	v_cvt_pk_bf16_f32 v131, v138, v139
	v_pk_mul_f32 v[138:139], v[136:137], v[88:89] op_sel_hi:[0,1]
	v_pk_mul_f32 v[150:151], v[136:137], v[90:91] op_sel_hi:[0,1]
	v_cvt_pk_bf16_f32 v138, v138, v139
	v_cvt_pk_bf16_f32 v139, v150, v151
	ds_write2_b64 v128, v[130:131], v[138:139] offset0:32 offset1:36
	v_pk_mul_f32 v[128:129], v[136:137], v[84:85] op_sel_hi:[0,1]
	v_pk_mul_f32 v[130:131], v[136:137], v[86:87] op_sel_hi:[0,1]
	v_cvt_pk_bf16_f32 v128, v128, v129
	v_cvt_pk_bf16_f32 v129, v130, v131
	v_pk_mul_f32 v[130:131], v[136:137], v[80:81] op_sel_hi:[0,1]
	v_pk_mul_f32 v[138:139], v[136:137], v[82:83] op_sel_hi:[0,1]
	v_cvt_pk_bf16_f32 v130, v130, v131
	v_cvt_pk_bf16_f32 v131, v138, v139
	ds_write2_b64 v132, v[128:129], v[130:131] offset0:64 offset1:68
	v_pk_mul_f32 v[128:129], v[136:137], v[76:77] op_sel_hi:[0,1]
	v_pk_mul_f32 v[130:131], v[136:137], v[78:79] op_sel_hi:[0,1]
	v_cvt_pk_bf16_f32 v128, v128, v129
	v_cvt_pk_bf16_f32 v129, v130, v131
	v_pk_mul_f32 v[130:131], v[136:137], v[72:73] op_sel_hi:[0,1]
	v_pk_mul_f32 v[138:139], v[136:137], v[74:75] op_sel_hi:[0,1]
	v_cvt_pk_bf16_f32 v130, v130, v131
	v_cvt_pk_bf16_f32 v131, v138, v139
	ds_write2_b64 v137, v[128:129], v[130:131] offset0:96 offset1:100
	v_pk_mul_f32 v[128:129], v[136:137], v[68:69] op_sel_hi:[0,1]
	v_pk_mul_f32 v[130:131], v[136:137], v[70:71] op_sel_hi:[0,1]
	v_cvt_pk_bf16_f32 v128, v128, v129
	v_cvt_pk_bf16_f32 v129, v130, v131
	v_pk_mul_f32 v[130:131], v[136:137], v[64:65] op_sel_hi:[0,1]
	v_pk_mul_f32 v[138:139], v[136:137], v[66:67] op_sel_hi:[0,1]
	v_cvt_pk_bf16_f32 v130, v130, v131
	v_cvt_pk_bf16_f32 v131, v138, v139
	s_and_b64 vcc, exec, s[30:31]
	s_mov_b64 s[0:1], s[60:61]
	ds_write2_b64 v149, v[128:129], v[130:131] offset0:128 offset1:132
	s_waitcnt lgkmcnt(0)
	s_barrier
	s_cbranch_vccz .LBB0_147
	s_cmp_lt_i32 s46, 3
	s_cbranch_scc1 .LBB0_142
	s_cmp_gt_i32 s46, 3
	s_mov_b64 s[42:43], 0
	s_mov_b64 s[0:1], s[66:67]
	s_mov_b64 s[36:37], 0
	s_cbranch_scc0 .LBB0_143
	s_cmp_eq_u32 s46, 4
	s_mov_b64 s[36:37], -1
	s_cbranch_scc0 .LBB0_143
	s_mov_b64 s[36:37], 0
	s_mov_b64 s[0:1], s[68:69]
	s_branch .LBB0_143

.LBB0_147:
	s_lshl_b32 s2, s88, 1
	s_add_u32 s0, s0, s2
	s_addc_u32 s1, s1, 0
	v_lshlrev_b32_e32 v132, 1, v143
	v_lshl_add_u64 v[138:139], s[0:1], 0, v[132:133]
	v_cmp_lt_u32_e32 vcc, 447, v135
	v_mov_b32_e32 v250, 0x8000
	v_mov_b32_e32 v251, 0x10020
	v_cndmask_b32_e32 v250, v250, v251, vcc
	v_add_u32_e32 v246, v134, v250
	v_add_u32_e32 v247, 0x10020, v134
	v_ashrrev_i32_e32 v251, 5, v135
	v_mad_u32_u24 v252, v251, s89, v134
	ds_read_b128 v[206:209], v252 offset:32768
	v_add_u32_e32 v250, 0x200, v135
	v_ashrrev_i32_e32 v251, 5, v250
	v_mad_u32_u24 v252, v251, s89, v134
	ds_read_b128 v[210:213], v252 offset:32768
	v_add_u32_e32 v250, 0x400, v135
	v_ashrrev_i32_e32 v251, 5, v250
	v_mad_u32_u24 v252, v251, s89, v134
	ds_read_b128 v[214:217], v252 offset:32768
	v_add_u32_e32 v250, 0x600, v135
	v_ashrrev_i32_e32 v251, 5, v250
	v_mad_u32_u24 v252, v251, s89, v246
	ds_read_b128 v[218:221], v252
	v_add_u32_e32 v250, 0x800, v135
	v_ashrrev_i32_e32 v251, 5, v250
	v_mad_u32_u24 v252, v251, s89, v247
	ds_read_b128 v[222:225], v252
	v_add_u32_e32 v250, 0xa00, v135
	v_ashrrev_i32_e32 v251, 5, v250
	v_mad_u32_u24 v252, v251, s89, v247
	ds_read_b128 v[226:229], v252
	v_add_u32_e32 v250, 0xc00, v135
	v_ashrrev_i32_e32 v251, 5, v250
	v_mad_u32_u24 v252, v251, s89, v247
	ds_read_b128 v[230:233], v252
	v_add_u32_e32 v250, 0xe00, v135
	v_ashrrev_i32_e32 v251, 5, v250
	v_mad_u32_u24 v252, v251, s89, v247
	ds_read_b128 v[234:237], v252
	v_ashrrev_i32_e32 v251, 5, v135
	v_add_u32_e32 v252, s97, v251
	v_ashrrev_i32_e32 v253, 31, v252
	v_lshlrev_b64 v[252:253], 11, v[252:253]
	v_lshl_add_u64 v[252:253], v[138:139], 0, v[252:253]
	s_waitcnt lgkmcnt(7)
	global_store_dwordx4 v[252:253], v[206:209], off
	v_add_u32_e32 v250, 0x200, v135
	v_ashrrev_i32_e32 v251, 5, v250
	v_add_u32_e32 v252, s97, v251
	v_ashrrev_i32_e32 v253, 31, v252
	v_lshlrev_b64 v[252:253], 11, v[252:253]
	v_lshl_add_u64 v[252:253], v[138:139], 0, v[252:253]
	s_waitcnt lgkmcnt(6)
	global_store_dwordx4 v[252:253], v[210:213], off
	v_add_u32_e32 v250, 0x400, v135
	v_ashrrev_i32_e32 v251, 5, v250
	v_add_u32_e32 v252, s97, v251
	v_ashrrev_i32_e32 v253, 31, v252
	v_lshlrev_b64 v[252:253], 11, v[252:253]
	v_lshl_add_u64 v[252:253], v[138:139], 0, v[252:253]
	s_waitcnt lgkmcnt(5)
	global_store_dwordx4 v[252:253], v[214:217], off
	v_add_u32_e32 v250, 0x600, v135
	v_ashrrev_i32_e32 v251, 5, v250
	v_add_u32_e32 v252, s97, v251
	v_ashrrev_i32_e32 v253, 31, v252
	v_lshlrev_b64 v[252:253], 11, v[252:253]
	v_lshl_add_u64 v[252:253], v[138:139], 0, v[252:253]
	s_waitcnt lgkmcnt(4)
	global_store_dwordx4 v[252:253], v[218:221], off
	v_add_u32_e32 v250, 0x800, v135
	v_ashrrev_i32_e32 v251, 5, v250
	v_add_u32_e32 v252, s97, v251
	v_ashrrev_i32_e32 v253, 31, v252
	v_lshlrev_b64 v[252:253], 11, v[252:253]
	v_lshl_add_u64 v[252:253], v[138:139], 0, v[252:253]
	s_waitcnt lgkmcnt(3)
	global_store_dwordx4 v[252:253], v[222:225], off
	v_add_u32_e32 v250, 0xa00, v135
	v_ashrrev_i32_e32 v251, 5, v250
	v_add_u32_e32 v252, s97, v251
	v_ashrrev_i32_e32 v253, 31, v252
	v_lshlrev_b64 v[252:253], 11, v[252:253]
	v_lshl_add_u64 v[252:253], v[138:139], 0, v[252:253]
	s_waitcnt lgkmcnt(2)
	global_store_dwordx4 v[252:253], v[226:229], off
	v_add_u32_e32 v250, 0xc00, v135
	v_ashrrev_i32_e32 v251, 5, v250
	v_add_u32_e32 v252, s97, v251
	v_ashrrev_i32_e32 v253, 31, v252
	v_lshlrev_b64 v[252:253], 11, v[252:253]
	v_lshl_add_u64 v[252:253], v[138:139], 0, v[252:253]
	s_waitcnt lgkmcnt(1)
	global_store_dwordx4 v[252:253], v[230:233], off
	v_add_u32_e32 v250, 0xe00, v135
	v_ashrrev_i32_e32 v251, 5, v250
	v_add_u32_e32 v252, s97, v251
	v_ashrrev_i32_e32 v253, 31, v252
	v_lshlrev_b64 v[252:253], 11, v[252:253]
	v_lshl_add_u64 v[252:253], v[138:139], 0, v[252:253]
	s_waitcnt lgkmcnt(0)
	global_store_dwordx4 v[252:253], v[234:237], off
	v_mov_b32_e32 v137, 0
	s_and_b64 vcc, exec, s[28:29]
	s_cbranch_vccz .LBB0_163
	v_xor_b32_e32 v246, 1, v188
	v_lshlrev_b32_e32 v246, 2, v246
	v_xor_b32_e32 v247, 2, v188
	v_lshlrev_b32_e32 v247, 2, v247
	v_xor_b32_e32 v248, 4, v188
	v_lshlrev_b32_e32 v248, 2, v248
	v_xor_b32_e32 v249, 8, v188
	v_lshlrev_b32_e32 v249, 2, v249
	v_lshlrev_b32_e32 v251, 16, v207
	v_lshlrev_b32_e32 v250, 16, v206
	v_and_b32_e32 v207, 0xffff0000, v207
	v_and_b32_e32 v206, 0xffff0000, v206
	v_pk_mul_f32 v[206:207], v[206:207], v[206:207]
	s_nop 0
	v_pk_fma_f32 v[206:207], v[250:251], v[250:251], v[206:207]
	v_lshlrev_b32_e32 v251, 16, v209
	v_lshlrev_b32_e32 v250, 16, v208
	v_and_b32_e32 v209, 0xffff0000, v209
	v_and_b32_e32 v208, 0xffff0000, v208
	v_pk_mul_f32 v[208:209], v[208:209], v[208:209]
	s_nop 0
	v_pk_fma_f32 v[208:209], v[250:251], v[250:251], v[208:209]
	v_add_f32_e32 v206, v206, v207
	v_add_f32_e32 v206, v208, v206
	v_add_f32_e32 v206, v209, v206
	v_lshlrev_b32_e32 v251, 16, v211
	v_lshlrev_b32_e32 v250, 16, v210
	v_and_b32_e32 v211, 0xffff0000, v211
	v_and_b32_e32 v210, 0xffff0000, v210
	v_pk_mul_f32 v[210:211], v[210:211], v[210:211]
	s_nop 0
	v_pk_fma_f32 v[210:211], v[250:251], v[250:251], v[210:211]
	v_lshlrev_b32_e32 v251, 16, v213
	v_lshlrev_b32_e32 v250, 16, v212
	v_and_b32_e32 v213, 0xffff0000, v213
	v_and_b32_e32 v212, 0xffff0000, v212
	v_pk_mul_f32 v[212:213], v[212:213], v[212:213]
	s_nop 0
	v_pk_fma_f32 v[212:213], v[250:251], v[250:251], v[212:213]
	v_add_f32_e32 v210, v210, v211
	v_add_f32_e32 v210, v212, v210
	v_add_f32_e32 v210, v213, v210
	v_lshlrev_b32_e32 v251, 16, v215
	v_lshlrev_b32_e32 v250, 16, v214
	v_and_b32_e32 v215, 0xffff0000, v215
	v_and_b32_e32 v214, 0xffff0000, v214
	v_pk_mul_f32 v[214:215], v[214:215], v[214:215]
	s_nop 0
	v_pk_fma_f32 v[214:215], v[250:251], v[250:251], v[214:215]
	v_lshlrev_b32_e32 v251, 16, v217
	v_lshlrev_b32_e32 v250, 16, v216
	v_and_b32_e32 v217, 0xffff0000, v217
	v_and_b32_e32 v216, 0xffff0000, v216
	v_pk_mul_f32 v[216:217], v[216:217], v[216:217]
	s_nop 0
	v_pk_fma_f32 v[216:217], v[250:251], v[250:251], v[216:217]
	v_add_f32_e32 v214, v214, v215
	v_add_f32_e32 v214, v216, v214
	v_add_f32_e32 v214, v217, v214
	v_lshlrev_b32_e32 v251, 16, v219
	v_lshlrev_b32_e32 v250, 16, v218
	v_and_b32_e32 v219, 0xffff0000, v219
	v_and_b32_e32 v218, 0xffff0000, v218
	v_pk_mul_f32 v[218:219], v[218:219], v[218:219]
	s_nop 0
	v_pk_fma_f32 v[218:219], v[250:251], v[250:251], v[218:219]
	v_lshlrev_b32_e32 v251, 16, v221
	v_lshlrev_b32_e32 v250, 16, v220
	v_and_b32_e32 v221, 0xffff0000, v221
	v_and_b32_e32 v220, 0xffff0000, v220
	v_pk_mul_f32 v[220:221], v[220:221], v[220:221]
	s_nop 0
	v_pk_fma_f32 v[220:221], v[250:251], v[250:251], v[220:221]
	v_add_f32_e32 v218, v218, v219
	v_add_f32_e32 v218, v220, v218
	v_add_f32_e32 v218, v221, v218
	v_lshlrev_b32_e32 v251, 16, v223
	v_lshlrev_b32_e32 v250, 16, v222
	v_and_b32_e32 v223, 0xffff0000, v223
	v_and_b32_e32 v222, 0xffff0000, v222
	v_pk_mul_f32 v[222:223], v[222:223], v[222:223]
	s_nop 0
	v_pk_fma_f32 v[222:223], v[250:251], v[250:251], v[222:223]
	v_lshlrev_b32_e32 v251, 16, v225
	v_lshlrev_b32_e32 v250, 16, v224
	v_and_b32_e32 v225, 0xffff0000, v225
	v_and_b32_e32 v224, 0xffff0000, v224
	v_pk_mul_f32 v[224:225], v[224:225], v[224:225]
	s_nop 0
	v_pk_fma_f32 v[224:225], v[250:251], v[250:251], v[224:225]
	v_add_f32_e32 v222, v222, v223
	v_add_f32_e32 v222, v224, v222
	v_add_f32_e32 v222, v225, v222
	v_lshlrev_b32_e32 v251, 16, v227
	v_lshlrev_b32_e32 v250, 16, v226
	v_and_b32_e32 v227, 0xffff0000, v227
	v_and_b32_e32 v226, 0xffff0000, v226
	v_pk_mul_f32 v[226:227], v[226:227], v[226:227]
	s_nop 0
	v_pk_fma_f32 v[226:227], v[250:251], v[250:251], v[226:227]
	v_lshlrev_b32_e32 v251, 16, v229
	v_lshlrev_b32_e32 v250, 16, v228
	v_and_b32_e32 v229, 0xffff0000, v229
	v_and_b32_e32 v228, 0xffff0000, v228
	v_pk_mul_f32 v[228:229], v[228:229], v[228:229]
	s_nop 0
	v_pk_fma_f32 v[228:229], v[250:251], v[250:251], v[228:229]
	v_add_f32_e32 v226, v226, v227
	v_add_f32_e32 v226, v228, v226
	v_add_f32_e32 v226, v229, v226
	v_lshlrev_b32_e32 v251, 16, v231
	v_lshlrev_b32_e32 v250, 16, v230
	v_and_b32_e32 v231, 0xffff0000, v231
	v_and_b32_e32 v230, 0xffff0000, v230
	v_pk_mul_f32 v[230:231], v[230:231], v[230:231]
	s_nop 0
	v_pk_fma_f32 v[230:231], v[250:251], v[250:251], v[230:231]
	v_lshlrev_b32_e32 v251, 16, v233
	v_lshlrev_b32_e32 v250, 16, v232
	v_and_b32_e32 v233, 0xffff0000, v233
	v_and_b32_e32 v232, 0xffff0000, v232
	v_pk_mul_f32 v[232:233], v[232:233], v[232:233]
	s_nop 0
	v_pk_fma_f32 v[232:233], v[250:251], v[250:251], v[232:233]
	v_add_f32_e32 v230, v230, v231
	v_add_f32_e32 v230, v232, v230
	v_add_f32_e32 v230, v233, v230
	v_lshlrev_b32_e32 v251, 16, v235
	v_lshlrev_b32_e32 v250, 16, v234
	v_and_b32_e32 v235, 0xffff0000, v235
	v_and_b32_e32 v234, 0xffff0000, v234
	v_pk_mul_f32 v[234:235], v[234:235], v[234:235]
	s_nop 0
	v_pk_fma_f32 v[234:235], v[250:251], v[250:251], v[234:235]
	v_lshlrev_b32_e32 v251, 16, v237
	v_lshlrev_b32_e32 v250, 16, v236
	v_and_b32_e32 v237, 0xffff0000, v237
	v_and_b32_e32 v236, 0xffff0000, v236
	v_pk_mul_f32 v[236:237], v[236:237], v[236:237]
	s_nop 0
	v_pk_fma_f32 v[236:237], v[250:251], v[250:251], v[236:237]
	v_add_f32_e32 v234, v234, v235
	v_add_f32_e32 v234, v236, v234
	v_add_f32_e32 v234, v237, v234
	ds_bpermute_b32 v238, v246, v206
	ds_bpermute_b32 v239, v246, v210
	ds_bpermute_b32 v240, v246, v214
	ds_bpermute_b32 v241, v246, v218
	ds_bpermute_b32 v242, v246, v222
	ds_bpermute_b32 v243, v246, v226
	ds_bpermute_b32 v244, v246, v230
	ds_bpermute_b32 v245, v246, v234
	s_waitcnt lgkmcnt(7)
	v_add_f32_e32 v206, v206, v238
	s_waitcnt lgkmcnt(6)
	v_add_f32_e32 v210, v210, v239
	s_waitcnt lgkmcnt(5)
	v_add_f32_e32 v214, v214, v240
	s_waitcnt lgkmcnt(4)
	v_add_f32_e32 v218, v218, v241
	s_waitcnt lgkmcnt(3)
	v_add_f32_e32 v222, v222, v242
	s_waitcnt lgkmcnt(2)
	v_add_f32_e32 v226, v226, v243
	s_waitcnt lgkmcnt(1)
	v_add_f32_e32 v230, v230, v244
	s_waitcnt lgkmcnt(0)
	v_add_f32_e32 v234, v234, v245
	ds_bpermute_b32 v238, v247, v206
	ds_bpermute_b32 v239, v247, v210
	ds_bpermute_b32 v240, v247, v214
	ds_bpermute_b32 v241, v247, v218
	ds_bpermute_b32 v242, v247, v222
	ds_bpermute_b32 v243, v247, v226
	ds_bpermute_b32 v244, v247, v230
	ds_bpermute_b32 v245, v247, v234
	s_waitcnt lgkmcnt(7)
	v_add_f32_e32 v206, v206, v238
	s_waitcnt lgkmcnt(6)
	v_add_f32_e32 v210, v210, v239
	s_waitcnt lgkmcnt(5)
	v_add_f32_e32 v214, v214, v240
	s_waitcnt lgkmcnt(4)
	v_add_f32_e32 v218, v218, v241
	s_waitcnt lgkmcnt(3)
	v_add_f32_e32 v222, v222, v242
	s_waitcnt lgkmcnt(2)
	v_add_f32_e32 v226, v226, v243
	s_waitcnt lgkmcnt(1)
	v_add_f32_e32 v230, v230, v244
	s_waitcnt lgkmcnt(0)
	v_add_f32_e32 v234, v234, v245
	ds_bpermute_b32 v238, v248, v206
	ds_bpermute_b32 v239, v248, v210
	ds_bpermute_b32 v240, v248, v214
	ds_bpermute_b32 v241, v248, v218
	ds_bpermute_b32 v242, v248, v222
	ds_bpermute_b32 v243, v248, v226
	ds_bpermute_b32 v244, v248, v230
	ds_bpermute_b32 v245, v248, v234
	s_waitcnt lgkmcnt(7)
	v_add_f32_e32 v206, v206, v238
	s_waitcnt lgkmcnt(6)
	v_add_f32_e32 v210, v210, v239
	s_waitcnt lgkmcnt(5)
	v_add_f32_e32 v214, v214, v240
	s_waitcnt lgkmcnt(4)
	v_add_f32_e32 v218, v218, v241
	s_waitcnt lgkmcnt(3)
	v_add_f32_e32 v222, v222, v242
	s_waitcnt lgkmcnt(2)
	v_add_f32_e32 v226, v226, v243
	s_waitcnt lgkmcnt(1)
	v_add_f32_e32 v230, v230, v244
	s_waitcnt lgkmcnt(0)
	v_add_f32_e32 v234, v234, v245
	ds_bpermute_b32 v238, v249, v206
	ds_bpermute_b32 v239, v249, v210
	ds_bpermute_b32 v240, v249, v214
	ds_bpermute_b32 v241, v249, v218
	ds_bpermute_b32 v242, v249, v222
	ds_bpermute_b32 v243, v249, v226
	ds_bpermute_b32 v244, v249, v230
	ds_bpermute_b32 v245, v249, v234
	s_waitcnt lgkmcnt(7)
	v_add_f32_e32 v206, v206, v238
	s_waitcnt lgkmcnt(6)
	v_add_f32_e32 v210, v210, v239
	s_waitcnt lgkmcnt(5)
	v_add_f32_e32 v214, v214, v240
	s_waitcnt lgkmcnt(4)
	v_add_f32_e32 v218, v218, v241
	s_waitcnt lgkmcnt(3)
	v_add_f32_e32 v222, v222, v242
	s_waitcnt lgkmcnt(2)
	v_add_f32_e32 v226, v226, v243
	s_waitcnt lgkmcnt(1)
	v_add_f32_e32 v230, v230, v244
	s_waitcnt lgkmcnt(0)
	v_add_f32_e32 v234, v234, v245
	v_max_f32_e32 v137, 0, v206
	v_max_f32_e32 v250, v137, v137
	v_max_f32_e32 v137, v250, v210
	v_max_f32_e32 v250, v137, v137
	v_max_f32_e32 v137, v250, v214
	v_max_f32_e32 v250, v137, v137
	v_max_f32_e32 v137, v250, v218
	v_max_f32_e32 v250, v137, v137
	v_max_f32_e32 v137, v250, v222
	v_max_f32_e32 v250, v137, v137
	v_max_f32_e32 v137, v250, v226
	v_max_f32_e32 v250, v137, v137
	v_max_f32_e32 v137, v250, v230
	v_max_f32_e32 v250, v137, v137
	v_max_f32_e32 v137, v250, v234

.LBB0_166:
	s_andn2_b64 vcc, exec, s[34:35]
	s_mov_b64 s[0:1], -1
	s_barrier
	s_cbranch_vccnz .LBB0_194
	v_pk_mul_f32 v[66:67], v[136:137], v[60:61] op_sel_hi:[0,1]
	v_pk_mul_f32 v[68:69], v[136:137], v[62:63] op_sel_hi:[0,1]
	v_cvt_pk_bf16_f32 v66, v66, v67
	v_cvt_pk_bf16_f32 v67, v68, v69
	v_pk_mul_f32 v[68:69], v[136:137], v[56:57] op_sel_hi:[0,1]
	v_pk_mul_f32 v[70:71], v[136:137], v[58:59] op_sel_hi:[0,1]
	v_mad_u64_u32 v[64:65], s[0:1], v160, s89, v[140:141]
	v_add_u32_e32 v64, v64, v205
	v_cvt_pk_bf16_f32 v68, v68, v69
	v_cvt_pk_bf16_f32 v69, v70, v71
	ds_write2_b64 v64, v[66:67], v[68:69] offset1:4
	v_pk_mul_f32 v[66:67], v[136:137], v[52:53] op_sel_hi:[0,1]
	v_pk_mul_f32 v[68:69], v[136:137], v[54:55] op_sel_hi:[0,1]
	v_cvt_pk_bf16_f32 v66, v66, v67
	v_cvt_pk_bf16_f32 v67, v68, v69
	v_pk_mul_f32 v[68:69], v[136:137], v[48:49] op_sel_hi:[0,1]
	v_pk_mul_f32 v[70:71], v[136:137], v[50:51] op_sel_hi:[0,1]
	v_cvt_pk_bf16_f32 v68, v68, v69
	v_cvt_pk_bf16_f32 v69, v70, v71
	v_add_u32_e32 v72, 0x2000, v64
	ds_write2_b64 v72, v[66:67], v[68:69] offset0:32 offset1:36
	v_pk_mul_f32 v[66:67], v[136:137], v[44:45] op_sel_hi:[0,1]
	v_pk_mul_f32 v[68:69], v[136:137], v[46:47] op_sel_hi:[0,1]
	v_cvt_pk_bf16_f32 v66, v66, v67
	v_cvt_pk_bf16_f32 v67, v68, v69
	v_pk_mul_f32 v[68:69], v[136:137], v[40:41] op_sel_hi:[0,1]
	v_pk_mul_f32 v[70:71], v[136:137], v[42:43] op_sel_hi:[0,1]
	v_cvt_pk_bf16_f32 v68, v68, v69
	v_cvt_pk_bf16_f32 v69, v70, v71
	v_add_u32_e32 v73, 0x4000, v64
	ds_write2_b64 v73, v[66:67], v[68:69] offset0:64 offset1:68
	v_pk_mul_f32 v[66:67], v[136:137], v[36:37] op_sel_hi:[0,1]
	v_pk_mul_f32 v[68:69], v[136:137], v[38:39] op_sel_hi:[0,1]
	v_cvt_pk_bf16_f32 v66, v66, v67
	v_cvt_pk_bf16_f32 v67, v68, v69
	v_pk_mul_f32 v[68:69], v[136:137], v[32:33] op_sel_hi:[0,1]
	v_pk_mul_f32 v[70:71], v[136:137], v[34:35] op_sel_hi:[0,1]
	v_cvt_pk_bf16_f32 v68, v68, v69
	v_cvt_pk_bf16_f32 v69, v70, v71
	v_add_u32_e32 v74, 0x6000, v64
	v_add_u32_e32 v74, v74, v254
	ds_write2_b64 v74, v[66:67], v[68:69] offset0:96 offset1:100
	v_pk_mul_f32 v[66:67], v[136:137], v[28:29] op_sel_hi:[0,1]
	v_pk_mul_f32 v[68:69], v[136:137], v[30:31] op_sel_hi:[0,1]
	v_cvt_pk_bf16_f32 v66, v66, v67
	v_cvt_pk_bf16_f32 v67, v68, v69
	v_pk_mul_f32 v[68:69], v[136:137], v[24:25] op_sel_hi:[0,1]
	v_pk_mul_f32 v[70:71], v[136:137], v[26:27] op_sel_hi:[0,1]
	v_cvt_pk_bf16_f32 v68, v68, v69
	v_cvt_pk_bf16_f32 v69, v70, v71
	ds_write2_b64 v64, v[66:67], v[68:69] offset0:32 offset1:36
	v_pk_mul_f32 v[64:65], v[136:137], v[20:21] op_sel_hi:[0,1]
	v_pk_mul_f32 v[66:67], v[136:137], v[22:23] op_sel_hi:[0,1]
	v_cvt_pk_bf16_f32 v64, v64, v65
	v_cvt_pk_bf16_f32 v65, v66, v67
	v_pk_mul_f32 v[66:67], v[136:137], v[16:17] op_sel_hi:[0,1]
	v_pk_mul_f32 v[68:69], v[136:137], v[18:19] op_sel_hi:[0,1]
	v_cvt_pk_bf16_f32 v66, v66, v67
	v_cvt_pk_bf16_f32 v67, v68, v69
	ds_write2_b64 v72, v[64:65], v[66:67] offset0:64 offset1:68
	v_pk_mul_f32 v[64:65], v[136:137], v[12:13] op_sel_hi:[0,1]
	v_pk_mul_f32 v[66:67], v[136:137], v[14:15] op_sel_hi:[0,1]
	v_cvt_pk_bf16_f32 v64, v64, v65
	v_cvt_pk_bf16_f32 v65, v66, v67
	v_pk_mul_f32 v[66:67], v[136:137], v[8:9] op_sel_hi:[0,1]
	v_pk_mul_f32 v[68:69], v[136:137], v[10:11] op_sel_hi:[0,1]
	v_cvt_pk_bf16_f32 v66, v66, v67
	v_cvt_pk_bf16_f32 v67, v68, v69
	ds_write2_b64 v73, v[64:65], v[66:67] offset0:96 offset1:100
	v_pk_mul_f32 v[64:65], v[136:137], v[4:5] op_sel_hi:[0,1]
	v_pk_mul_f32 v[66:67], v[136:137], v[6:7] op_sel_hi:[0,1]
	v_cvt_pk_bf16_f32 v64, v64, v65
	v_cvt_pk_bf16_f32 v65, v66, v67
	v_pk_mul_f32 v[66:67], v[136:137], v[0:1] op_sel_hi:[0,1]
	v_pk_mul_f32 v[68:69], v[136:137], v[2:3] op_sel_hi:[0,1]
	v_cvt_pk_bf16_f32 v66, v66, v67
	v_cvt_pk_bf16_f32 v67, v68, v69
	s_andn2_b64 vcc, exec, s[30:31]
	s_mov_b64 s[0:1], s[60:61]
	ds_write2_b64 v74, v[64:65], v[66:67] offset0:128 offset1:132
	s_waitcnt lgkmcnt(0)
	s_barrier
	s_cbranch_vccnz .LBB0_177
	s_cmp_lt_i32 s46, 3
	s_cbranch_scc1 .LBB0_172
	s_cmp_gt_i32 s46, 3
	s_mov_b64 s[34:35], 0
	s_mov_b64 s[0:1], s[66:67]
	s_mov_b64 s[30:31], 0
	s_cbranch_scc0 .LBB0_173
	s_cmp_eq_u32 s46, 4
	s_mov_b64 s[30:31], -1
	s_cbranch_scc0 .LBB0_173
	s_mov_b64 s[30:31], 0
	s_mov_b64 s[0:1], s[68:69]
	s_branch .LBB0_173

.LBB0_177:
	s_bitset1_b32 s97, 7
	s_lshl_b32 s4, s88, 1
	s_add_u32 s0, s0, s4
	s_addc_u32 s1, s1, 0
	v_lshlrev_b32_e32 v132, 1, v143
	v_ashrrev_i32_e32 v70, 5, v135
	v_lshl_add_u64 v[68:69], s[0:1], 0, v[132:133]
	v_cmp_lt_u32_e32 vcc, 447, v135
	v_mov_b32_e32 v250, 0x8000
	v_mov_b32_e32 v251, 0x10020
	v_cndmask_b32_e32 v250, v250, v251, vcc
	v_add_u32_e32 v246, v134, v250
	v_add_u32_e32 v247, 0x10020, v134
	v_ashrrev_i32_e32 v251, 5, v135
	v_mad_u32_u24 v252, v251, s89, v134
	ds_read_b128 v[206:209], v252 offset:32768
	v_add_u32_e32 v250, 0x200, v135
	v_ashrrev_i32_e32 v251, 5, v250
	v_mad_u32_u24 v252, v251, s89, v134
	ds_read_b128 v[210:213], v252 offset:32768
	v_add_u32_e32 v250, 0x400, v135
	v_ashrrev_i32_e32 v251, 5, v250
	v_mad_u32_u24 v252, v251, s89, v134
	ds_read_b128 v[214:217], v252 offset:32768
	v_add_u32_e32 v250, 0x600, v135
	v_ashrrev_i32_e32 v251, 5, v250
	v_mad_u32_u24 v252, v251, s89, v246
	ds_read_b128 v[218:221], v252
	v_add_u32_e32 v250, 0x800, v135
	v_ashrrev_i32_e32 v251, 5, v250
	v_mad_u32_u24 v252, v251, s89, v247
	ds_read_b128 v[222:225], v252
	v_add_u32_e32 v250, 0xa00, v135
	v_ashrrev_i32_e32 v251, 5, v250
	v_mad_u32_u24 v252, v251, s89, v247
	ds_read_b128 v[226:229], v252
	v_add_u32_e32 v250, 0xc00, v135
	v_ashrrev_i32_e32 v251, 5, v250
	v_mad_u32_u24 v252, v251, s89, v247
	ds_read_b128 v[230:233], v252
	v_add_u32_e32 v250, 0xe00, v135
	v_ashrrev_i32_e32 v251, 5, v250
	v_mad_u32_u24 v252, v251, s89, v247
	ds_read_b128 v[234:237], v252
	v_ashrrev_i32_e32 v251, 5, v135
	v_add_u32_e32 v252, s97, v251
	v_ashrrev_i32_e32 v253, 31, v252
	v_lshlrev_b64 v[252:253], 11, v[252:253]
	v_lshl_add_u64 v[252:253], v[68:69], 0, v[252:253]
	s_waitcnt lgkmcnt(7)
	global_store_dwordx4 v[252:253], v[206:209], off
	v_add_u32_e32 v250, 0x200, v135
	v_ashrrev_i32_e32 v251, 5, v250
	v_add_u32_e32 v252, s97, v251
	v_ashrrev_i32_e32 v253, 31, v252
	v_lshlrev_b64 v[252:253], 11, v[252:253]
	v_lshl_add_u64 v[252:253], v[68:69], 0, v[252:253]
	s_waitcnt lgkmcnt(6)
	global_store_dwordx4 v[252:253], v[210:213], off
	v_add_u32_e32 v250, 0x400, v135
	v_ashrrev_i32_e32 v251, 5, v250
	v_add_u32_e32 v252, s97, v251
	v_ashrrev_i32_e32 v253, 31, v252
	v_lshlrev_b64 v[252:253], 11, v[252:253]
	v_lshl_add_u64 v[252:253], v[68:69], 0, v[252:253]
	s_waitcnt lgkmcnt(5)
	global_store_dwordx4 v[252:253], v[214:217], off
	v_add_u32_e32 v250, 0x600, v135
	v_ashrrev_i32_e32 v251, 5, v250
	v_add_u32_e32 v252, s97, v251
	v_ashrrev_i32_e32 v253, 31, v252
	v_lshlrev_b64 v[252:253], 11, v[252:253]
	v_lshl_add_u64 v[252:253], v[68:69], 0, v[252:253]
	s_waitcnt lgkmcnt(4)
	global_store_dwordx4 v[252:253], v[218:221], off
	v_add_u32_e32 v250, 0x800, v135
	v_ashrrev_i32_e32 v251, 5, v250
	v_add_u32_e32 v252, s97, v251
	v_ashrrev_i32_e32 v253, 31, v252
	v_lshlrev_b64 v[252:253], 11, v[252:253]
	v_lshl_add_u64 v[252:253], v[68:69], 0, v[252:253]
	s_waitcnt lgkmcnt(3)
	global_store_dwordx4 v[252:253], v[222:225], off
	v_add_u32_e32 v250, 0xa00, v135
	v_ashrrev_i32_e32 v251, 5, v250
	v_add_u32_e32 v252, s97, v251
	v_ashrrev_i32_e32 v253, 31, v252
	v_lshlrev_b64 v[252:253], 11, v[252:253]
	v_lshl_add_u64 v[252:253], v[68:69], 0, v[252:253]
	s_waitcnt lgkmcnt(2)
	global_store_dwordx4 v[252:253], v[226:229], off
	v_add_u32_e32 v250, 0xc00, v135
	v_ashrrev_i32_e32 v251, 5, v250
	v_add_u32_e32 v252, s97, v251
	v_ashrrev_i32_e32 v253, 31, v252
	v_lshlrev_b64 v[252:253], 11, v[252:253]
	v_lshl_add_u64 v[252:253], v[68:69], 0, v[252:253]
	s_waitcnt lgkmcnt(1)
	global_store_dwordx4 v[252:253], v[230:233], off
	v_add_u32_e32 v250, 0xe00, v135
	v_ashrrev_i32_e32 v251, 5, v250
	v_add_u32_e32 v252, s97, v251
	v_ashrrev_i32_e32 v253, 31, v252
	v_lshlrev_b64 v[252:253], 11, v[252:253]
	v_lshl_add_u64 v[252:253], v[68:69], 0, v[252:253]
	s_waitcnt lgkmcnt(0)
	global_store_dwordx4 v[252:253], v[234:237], off
	v_mov_b32_e32 v70, v137
	s_and_b64 vcc, exec, s[28:29]
	s_cbranch_vccz .LBB0_193
	v_xor_b32_e32 v246, 1, v188
	v_lshlrev_b32_e32 v246, 2, v246
	v_xor_b32_e32 v247, 2, v188
	v_lshlrev_b32_e32 v247, 2, v247
	v_xor_b32_e32 v248, 4, v188
	v_lshlrev_b32_e32 v248, 2, v248
	v_xor_b32_e32 v249, 8, v188
	v_lshlrev_b32_e32 v249, 2, v249
	v_lshlrev_b32_e32 v251, 16, v207
	v_lshlrev_b32_e32 v250, 16, v206
	v_and_b32_e32 v207, 0xffff0000, v207
	v_and_b32_e32 v206, 0xffff0000, v206
	v_pk_mul_f32 v[206:207], v[206:207], v[206:207]
	s_nop 0
	v_pk_fma_f32 v[206:207], v[250:251], v[250:251], v[206:207]
	v_lshlrev_b32_e32 v251, 16, v209
	v_lshlrev_b32_e32 v250, 16, v208
	v_and_b32_e32 v209, 0xffff0000, v209
	v_and_b32_e32 v208, 0xffff0000, v208
	v_pk_mul_f32 v[208:209], v[208:209], v[208:209]
	s_nop 0
	v_pk_fma_f32 v[208:209], v[250:251], v[250:251], v[208:209]
	v_add_f32_e32 v206, v206, v207
	v_add_f32_e32 v206, v208, v206
	v_add_f32_e32 v206, v209, v206
	v_lshlrev_b32_e32 v251, 16, v211
	v_lshlrev_b32_e32 v250, 16, v210
	v_and_b32_e32 v211, 0xffff0000, v211
	v_and_b32_e32 v210, 0xffff0000, v210
	v_pk_mul_f32 v[210:211], v[210:211], v[210:211]
	s_nop 0
	v_pk_fma_f32 v[210:211], v[250:251], v[250:251], v[210:211]
	v_lshlrev_b32_e32 v251, 16, v213
	v_lshlrev_b32_e32 v250, 16, v212
	v_and_b32_e32 v213, 0xffff0000, v213
	v_and_b32_e32 v212, 0xffff0000, v212
	v_pk_mul_f32 v[212:213], v[212:213], v[212:213]
	s_nop 0
	v_pk_fma_f32 v[212:213], v[250:251], v[250:251], v[212:213]
	v_add_f32_e32 v210, v210, v211
	v_add_f32_e32 v210, v212, v210
	v_add_f32_e32 v210, v213, v210
	v_lshlrev_b32_e32 v251, 16, v215
	v_lshlrev_b32_e32 v250, 16, v214
	v_and_b32_e32 v215, 0xffff0000, v215
	v_and_b32_e32 v214, 0xffff0000, v214
	v_pk_mul_f32 v[214:215], v[214:215], v[214:215]
	s_nop 0
	v_pk_fma_f32 v[214:215], v[250:251], v[250:251], v[214:215]
	v_lshlrev_b32_e32 v251, 16, v217
	v_lshlrev_b32_e32 v250, 16, v216
	v_and_b32_e32 v217, 0xffff0000, v217
	v_and_b32_e32 v216, 0xffff0000, v216
	v_pk_mul_f32 v[216:217], v[216:217], v[216:217]
	s_nop 0
	v_pk_fma_f32 v[216:217], v[250:251], v[250:251], v[216:217]
	v_add_f32_e32 v214, v214, v215
	v_add_f32_e32 v214, v216, v214
	v_add_f32_e32 v214, v217, v214
	v_lshlrev_b32_e32 v251, 16, v219
	v_lshlrev_b32_e32 v250, 16, v218
	v_and_b32_e32 v219, 0xffff0000, v219
	v_and_b32_e32 v218, 0xffff0000, v218
	v_pk_mul_f32 v[218:219], v[218:219], v[218:219]
	s_nop 0
	v_pk_fma_f32 v[218:219], v[250:251], v[250:251], v[218:219]
	v_lshlrev_b32_e32 v251, 16, v221
	v_lshlrev_b32_e32 v250, 16, v220
	v_and_b32_e32 v221, 0xffff0000, v221
	v_and_b32_e32 v220, 0xffff0000, v220
	v_pk_mul_f32 v[220:221], v[220:221], v[220:221]
	s_nop 0
	v_pk_fma_f32 v[220:221], v[250:251], v[250:251], v[220:221]
	v_add_f32_e32 v218, v218, v219
	v_add_f32_e32 v218, v220, v218
	v_add_f32_e32 v218, v221, v218
	v_lshlrev_b32_e32 v251, 16, v223
	v_lshlrev_b32_e32 v250, 16, v222
	v_and_b32_e32 v223, 0xffff0000, v223
	v_and_b32_e32 v222, 0xffff0000, v222
	v_pk_mul_f32 v[222:223], v[222:223], v[222:223]
	s_nop 0
	v_pk_fma_f32 v[222:223], v[250:251], v[250:251], v[222:223]
	v_lshlrev_b32_e32 v251, 16, v225
	v_lshlrev_b32_e32 v250, 16, v224
	v_and_b32_e32 v225, 0xffff0000, v225
	v_and_b32_e32 v224, 0xffff0000, v224
	v_pk_mul_f32 v[224:225], v[224:225], v[224:225]
	s_nop 0
	v_pk_fma_f32 v[224:225], v[250:251], v[250:251], v[224:225]
	v_add_f32_e32 v222, v222, v223
	v_add_f32_e32 v222, v224, v222
	v_add_f32_e32 v222, v225, v222
	v_lshlrev_b32_e32 v251, 16, v227
	v_lshlrev_b32_e32 v250, 16, v226
	v_and_b32_e32 v227, 0xffff0000, v227
	v_and_b32_e32 v226, 0xffff0000, v226
	v_pk_mul_f32 v[226:227], v[226:227], v[226:227]
	s_nop 0
	v_pk_fma_f32 v[226:227], v[250:251], v[250:251], v[226:227]
	v_lshlrev_b32_e32 v251, 16, v229
	v_lshlrev_b32_e32 v250, 16, v228
	v_and_b32_e32 v229, 0xffff0000, v229
	v_and_b32_e32 v228, 0xffff0000, v228
	v_pk_mul_f32 v[228:229], v[228:229], v[228:229]
	s_nop 0
	v_pk_fma_f32 v[228:229], v[250:251], v[250:251], v[228:229]
	v_add_f32_e32 v226, v226, v227
	v_add_f32_e32 v226, v228, v226
	v_add_f32_e32 v226, v229, v226
	v_lshlrev_b32_e32 v251, 16, v231
	v_lshlrev_b32_e32 v250, 16, v230
	v_and_b32_e32 v231, 0xffff0000, v231
	v_and_b32_e32 v230, 0xffff0000, v230
	v_pk_mul_f32 v[230:231], v[230:231], v[230:231]
	s_nop 0
	v_pk_fma_f32 v[230:231], v[250:251], v[250:251], v[230:231]
	v_lshlrev_b32_e32 v251, 16, v233
	v_lshlrev_b32_e32 v250, 16, v232
	v_and_b32_e32 v233, 0xffff0000, v233
	v_and_b32_e32 v232, 0xffff0000, v232
	v_pk_mul_f32 v[232:233], v[232:233], v[232:233]
	s_nop 0
	v_pk_fma_f32 v[232:233], v[250:251], v[250:251], v[232:233]
	v_add_f32_e32 v230, v230, v231
	v_add_f32_e32 v230, v232, v230
	v_add_f32_e32 v230, v233, v230
	v_lshlrev_b32_e32 v251, 16, v235
	v_lshlrev_b32_e32 v250, 16, v234
	v_and_b32_e32 v235, 0xffff0000, v235
	v_and_b32_e32 v234, 0xffff0000, v234
	v_pk_mul_f32 v[234:235], v[234:235], v[234:235]
	s_nop 0
	v_pk_fma_f32 v[234:235], v[250:251], v[250:251], v[234:235]
	v_lshlrev_b32_e32 v251, 16, v237
	v_lshlrev_b32_e32 v250, 16, v236
	v_and_b32_e32 v237, 0xffff0000, v237
	v_and_b32_e32 v236, 0xffff0000, v236
	v_pk_mul_f32 v[236:237], v[236:237], v[236:237]
	s_nop 0
	v_pk_fma_f32 v[236:237], v[250:251], v[250:251], v[236:237]
	v_add_f32_e32 v234, v234, v235
	v_add_f32_e32 v234, v236, v234
	v_add_f32_e32 v234, v237, v234
	ds_bpermute_b32 v238, v246, v206
	ds_bpermute_b32 v239, v246, v210
	ds_bpermute_b32 v240, v246, v214
	ds_bpermute_b32 v241, v246, v218
	ds_bpermute_b32 v242, v246, v222
	ds_bpermute_b32 v243, v246, v226
	ds_bpermute_b32 v244, v246, v230
	ds_bpermute_b32 v245, v246, v234
	s_waitcnt lgkmcnt(7)
	v_add_f32_e32 v206, v206, v238
	s_waitcnt lgkmcnt(6)
	v_add_f32_e32 v210, v210, v239
	s_waitcnt lgkmcnt(5)
	v_add_f32_e32 v214, v214, v240
	s_waitcnt lgkmcnt(4)
	v_add_f32_e32 v218, v218, v241
	s_waitcnt lgkmcnt(3)
	v_add_f32_e32 v222, v222, v242
	s_waitcnt lgkmcnt(2)
	v_add_f32_e32 v226, v226, v243
	s_waitcnt lgkmcnt(1)
	v_add_f32_e32 v230, v230, v244
	s_waitcnt lgkmcnt(0)
	v_add_f32_e32 v234, v234, v245
	ds_bpermute_b32 v238, v247, v206
	ds_bpermute_b32 v239, v247, v210
	ds_bpermute_b32 v240, v247, v214
	ds_bpermute_b32 v241, v247, v218
	ds_bpermute_b32 v242, v247, v222
	ds_bpermute_b32 v243, v247, v226
	ds_bpermute_b32 v244, v247, v230
	ds_bpermute_b32 v245, v247, v234
	s_waitcnt lgkmcnt(7)
	v_add_f32_e32 v206, v206, v238
	s_waitcnt lgkmcnt(6)
	v_add_f32_e32 v210, v210, v239
	s_waitcnt lgkmcnt(5)
	v_add_f32_e32 v214, v214, v240
	s_waitcnt lgkmcnt(4)
	v_add_f32_e32 v218, v218, v241
	s_waitcnt lgkmcnt(3)
	v_add_f32_e32 v222, v222, v242
	s_waitcnt lgkmcnt(2)
	v_add_f32_e32 v226, v226, v243
	s_waitcnt lgkmcnt(1)
	v_add_f32_e32 v230, v230, v244
	s_waitcnt lgkmcnt(0)
	v_add_f32_e32 v234, v234, v245
	ds_bpermute_b32 v238, v248, v206
	ds_bpermute_b32 v239, v248, v210
	ds_bpermute_b32 v240, v248, v214
	ds_bpermute_b32 v241, v248, v218
	ds_bpermute_b32 v242, v248, v222
	ds_bpermute_b32 v243, v248, v226
	ds_bpermute_b32 v244, v248, v230
	ds_bpermute_b32 v245, v248, v234
	s_waitcnt lgkmcnt(7)
	v_add_f32_e32 v206, v206, v238
	s_waitcnt lgkmcnt(6)
	v_add_f32_e32 v210, v210, v239
	s_waitcnt lgkmcnt(5)
	v_add_f32_e32 v214, v214, v240
	s_waitcnt lgkmcnt(4)
	v_add_f32_e32 v218, v218, v241
	s_waitcnt lgkmcnt(3)
	v_add_f32_e32 v222, v222, v242
	s_waitcnt lgkmcnt(2)
	v_add_f32_e32 v226, v226, v243
	s_waitcnt lgkmcnt(1)
	v_add_f32_e32 v230, v230, v244
	s_waitcnt lgkmcnt(0)
	v_add_f32_e32 v234, v234, v245
	ds_bpermute_b32 v238, v249, v206
	ds_bpermute_b32 v239, v249, v210
	ds_bpermute_b32 v240, v249, v214
	ds_bpermute_b32 v241, v249, v218
	ds_bpermute_b32 v242, v249, v222
	ds_bpermute_b32 v243, v249, v226
	ds_bpermute_b32 v244, v249, v230
	ds_bpermute_b32 v245, v249, v234
	s_waitcnt lgkmcnt(7)
	v_add_f32_e32 v206, v206, v238
	s_waitcnt lgkmcnt(6)
	v_add_f32_e32 v210, v210, v239
	s_waitcnt lgkmcnt(5)
	v_add_f32_e32 v214, v214, v240
	s_waitcnt lgkmcnt(4)
	v_add_f32_e32 v218, v218, v241
	s_waitcnt lgkmcnt(3)
	v_add_f32_e32 v222, v222, v242
	s_waitcnt lgkmcnt(2)
	v_add_f32_e32 v226, v226, v243
	s_waitcnt lgkmcnt(1)
	v_add_f32_e32 v230, v230, v244
	s_waitcnt lgkmcnt(0)
	v_add_f32_e32 v234, v234, v245
	v_max_f32_e32 v250, v137, v137
	v_max_f32_e32 v70, v250, v206
	v_max_f32_e32 v250, v70, v70
	v_max_f32_e32 v70, v250, v210
	v_max_f32_e32 v250, v70, v70
	v_max_f32_e32 v70, v250, v214
	v_max_f32_e32 v250, v70, v70
	v_max_f32_e32 v70, v250, v218
	v_max_f32_e32 v250, v70, v70
	v_max_f32_e32 v70, v250, v222
	v_max_f32_e32 v250, v70, v70
	v_max_f32_e32 v70, v250, v226
	v_max_f32_e32 v250, v70, v70
	v_max_f32_e32 v70, v250, v230
	v_max_f32_e32 v250, v70, v70
	v_max_f32_e32 v70, v250, v234
